# v13 plus: row LayerNorm loops use packed f32 ops
# baseline (speedup 1.0000x reference)
; __device__ __forceinline__ unsigned cvt_pk_bf16(float lo, float hi) { const f32x2c v = {lo, hi}; const bf16x2c b = __builtin_convertvector(v, bf16x2c); return __builtin_bit_cast(unsigned, b); }
; __device__ __forceinline__ float bflo(unsigned u) { return __uint_as_float(u << 16); }
; __device__ __forceinline__ float bfhi(unsigned u) { return __uint_as_float(u & 0xffff0000u); }
; __device__ void phase_ln(KP p, const float* g, const float* b, bool final_out, int tid_in, int r0, int r1, int b0) {
;     ...
;     for (int row = r0 + gw; row < r1; row += nw) {
;         bf16_t* xr = Xb + (size_t)row * 1024 + lane * 8;
;         f32x4 x[4]; float s = 0.f;
; #pragma unroll
;         for (int j = 0; j < 2; ++j) { const u32x4v u = *(const u32x4v*)(xr + 512 * j);
;             x[2 * j] = (f32x4){bflo(u[0]), bfhi(u[0]), bflo(u[1]), bfhi(u[1])}; x[2 * j + 1] = (f32x4){bflo(u[2]), bfhi(u[2]), bflo(u[3]), bfhi(u[3])}; }
; #pragma unroll
;         for (int j = 0; j < 4; ++j) s += x[j][0] + x[j][1] + x[j][2] + x[j][3];
;         const float mu = wave_sum(s, lane) * (1.f / 1024.f); float v = 0.f;
; #pragma unroll
;         for (int j = 0; j < 4; ++j) { x[j] = x[j] - mu; v += x[j][0] * x[j][0] + x[j][1] * x[j][1] + x[j][2] * x[j][2] + x[j][3] * x[j][3]; }
;         const float r = rsqrtf(wave_sum(v, lane) * (1.f / 1024.f) + LN_EPS);
; #pragma unroll
;         for (int j = 0; j < 2; ++j) {
;             const f32x4 y0 = x[2 * j] * r * gv[2 * j] + bv[2 * j], y1 = x[2 * j + 1] * r * gv[2 * j + 1] + bv[2 * j + 1];
;             if (final_out) { float* yo = p->out + (size_t)row * 1024 + lane * 8 + 512 * j; __builtin_nontemporal_store(y0, (f32x4*)yo); __builtin_nontemporal_store(y1, (f32x4*)(yo + 4)); }
;             else { u32x4v o; o[0] = cvt_pk_bf16(y0[0], y0[1]); o[1] = cvt_pk_bf16(y0[2], y0[3]); o[2] = cvt_pk_bf16(y1[0], y1[1]); o[3] = cvt_pk_bf16(y1[2], y1[3]);
;                 *(u32x4v*)(xr + 512 * j) = o; }
;         }
;     }
.LBB0_773:
	global_load_dwordx4 v[40:43], v[36:37], off
	global_load_dwordx4 v[44:47], v[36:37], off offset:1024
	v_mov_b32_e32 v66, 0xba800000
	s_waitcnt vmcnt(0)
.Lln1_loop:
	v_lshlrev_b32_e32 v48, 16, v40
	v_and_b32_e32 v49, 0xffff0000, v40
	v_lshlrev_b32_e32 v50, 16, v41
	v_and_b32_e32 v51, 0xffff0000, v41
	v_lshlrev_b32_e32 v52, 16, v42
	v_and_b32_e32 v53, 0xffff0000, v42
	v_lshlrev_b32_e32 v54, 16, v43
	v_and_b32_e32 v55, 0xffff0000, v43
	v_lshlrev_b32_e32 v56, 16, v44
	v_and_b32_e32 v57, 0xffff0000, v44
	v_lshlrev_b32_e32 v58, 16, v45
	v_and_b32_e32 v59, 0xffff0000, v45
	v_lshlrev_b32_e32 v60, 16, v46
	v_and_b32_e32 v61, 0xffff0000, v46
	v_lshlrev_b32_e32 v62, 16, v47
	v_and_b32_e32 v63, 0xffff0000, v47
	v_lshl_add_u64 v[38:39], v[36:37], 0, s[14:15]
	global_load_dwordx4 v[40:43], v[38:39], off
	global_load_dwordx4 v[44:47], v[38:39], off offset:1024
	v_pk_add_f32 v[64:65], v[48:49], v[50:51]
	v_pk_add_f32 v[64:65], v[64:65], v[52:53]
	v_pk_add_f32 v[64:65], v[64:65], v[54:55]
	v_pk_add_f32 v[64:65], v[64:65], v[56:57]
	v_pk_add_f32 v[64:65], v[64:65], v[58:59]
	v_pk_add_f32 v[64:65], v[64:65], v[60:61]
	v_pk_add_f32 v[64:65], v[64:65], v[62:63]
	v_add_f32_e32 v35, v64, v65
	s_nop 1
	v_add_f32_dpp v35, v35, v35 quad_perm:[1,0,3,2] row_mask:0xf bank_mask:0xf
	s_nop 1
	v_add_f32_dpp v35, v35, v35 quad_perm:[2,3,0,1] row_mask:0xf bank_mask:0xf
	s_nop 1
	v_add_f32_dpp v35, v35, v35 row_half_mirror row_mask:0xf bank_mask:0xf
	s_nop 1
	v_add_f32_dpp v35, v35, v35 row_mirror row_mask:0xf bank_mask:0xf
	s_nop 1
	v_readlane_b32 vcc_lo, v35, 0
	v_readlane_b32 vcc_hi, v35, 16
	s_nop 1
	v_mov_b32_e32 v8, vcc_lo
	v_add_f32_e32 v8, vcc_hi, v8
	v_readlane_b32 vcc_lo, v35, 32
	v_readlane_b32 vcc_hi, v35, 48
	s_nop 1
	v_add_f32_e32 v8, vcc_lo, v8
	v_add_f32_e32 v35, vcc_hi, v8
	v_mov_b32_e32 v8, v35
	v_mov_b32_e32 v64, v35
	v_pk_fma_f32 v[48:49], v[64:65], v[66:67], v[48:49] op_sel_hi:[0,0,1]
	v_pk_fma_f32 v[50:51], v[64:65], v[66:67], v[50:51] op_sel_hi:[0,0,1]
	v_pk_fma_f32 v[52:53], v[64:65], v[66:67], v[52:53] op_sel_hi:[0,0,1]
	v_pk_fma_f32 v[54:55], v[64:65], v[66:67], v[54:55] op_sel_hi:[0,0,1]
	v_pk_fma_f32 v[56:57], v[64:65], v[66:67], v[56:57] op_sel_hi:[0,0,1]
	v_pk_fma_f32 v[58:59], v[64:65], v[66:67], v[58:59] op_sel_hi:[0,0,1]
	v_pk_fma_f32 v[60:61], v[64:65], v[66:67], v[60:61] op_sel_hi:[0,0,1]
	v_pk_fma_f32 v[62:63], v[64:65], v[66:67], v[62:63] op_sel_hi:[0,0,1]
	v_pk_mul_f32 v[64:65], v[48:49], v[48:49]
	v_pk_fma_f32 v[64:65], v[50:51], v[50:51], v[64:65]
	v_pk_fma_f32 v[64:65], v[52:53], v[52:53], v[64:65]
	v_pk_fma_f32 v[64:65], v[54:55], v[54:55], v[64:65]
	v_pk_fma_f32 v[64:65], v[56:57], v[56:57], v[64:65]
	v_pk_fma_f32 v[64:65], v[58:59], v[58:59], v[64:65]
	v_pk_fma_f32 v[64:65], v[60:61], v[60:61], v[64:65]
	v_pk_fma_f32 v[64:65], v[62:63], v[62:63], v[64:65]
	v_add_f32_e32 v35, v64, v65
	s_nop 1
	v_add_f32_dpp v35, v35, v35 quad_perm:[1,0,3,2] row_mask:0xf bank_mask:0xf
	s_nop 1
	v_add_f32_dpp v35, v35, v35 quad_perm:[2,3,0,1] row_mask:0xf bank_mask:0xf
	s_nop 1
	v_add_f32_dpp v35, v35, v35 row_half_mirror row_mask:0xf bank_mask:0xf
	s_nop 1
	v_add_f32_dpp v35, v35, v35 row_mirror row_mask:0xf bank_mask:0xf
	s_nop 1
	v_readlane_b32 vcc_lo, v35, 0
	v_readlane_b32 vcc_hi, v35, 16
	s_nop 1
	v_mov_b32_e32 v8, vcc_lo
	v_add_f32_e32 v8, vcc_hi, v8
	v_readlane_b32 vcc_lo, v35, 32
	v_readlane_b32 vcc_hi, v35, 48
	s_nop 1
	v_add_f32_e32 v8, vcc_lo, v8
	v_add_f32_e32 v35, vcc_hi, v8
	v_fmamk_f32 v35, v35, 0x3a800000, v248
	v_cmp_gt_f32_e32 vcc, s96, v35
	v_mul_f32_e32 v8, 0x4b800000, v35
	s_nop 0
	v_cndmask_b32_e32 v35, v35, v8, vcc
	v_rsq_f32_e32 v35, v35
	s_nop 0
	v_mul_f32_e32 v8, 0x45800000, v35
	v_cndmask_b32_e32 v64, v35, v8, vcc
	v_pk_mul_f32 v[48:49], v[48:49], v[64:65] op_sel_hi:[1,0]
	v_pk_mul_f32 v[50:51], v[50:51], v[64:65] op_sel_hi:[1,0]
	v_pk_mul_f32 v[52:53], v[52:53], v[64:65] op_sel_hi:[1,0]
	v_pk_mul_f32 v[54:55], v[54:55], v[64:65] op_sel_hi:[1,0]
	v_pk_mul_f32 v[56:57], v[56:57], v[64:65] op_sel_hi:[1,0]
	v_pk_mul_f32 v[58:59], v[58:59], v[64:65] op_sel_hi:[1,0]
	v_pk_mul_f32 v[60:61], v[60:61], v[64:65] op_sel_hi:[1,0]
	v_pk_mul_f32 v[62:63], v[62:63], v[64:65] op_sel_hi:[1,0]
	v_pk_fma_f32 v[48:49], v[4:5], v[48:49], v[14:15]
	v_pk_fma_f32 v[50:51], v[6:7], v[50:51], v[16:17]
	v_pk_fma_f32 v[52:53], v[0:1], v[52:53], v[10:11]
	v_pk_fma_f32 v[54:55], v[2:3], v[54:55], v[12:13]
	v_pk_fma_f32 v[56:57], v[22:23], v[56:57], v[30:31]
	v_pk_fma_f32 v[58:59], v[24:25], v[58:59], v[32:33]
	v_pk_fma_f32 v[60:61], v[18:19], v[60:61], v[26:27]
	v_pk_fma_f32 v[62:63], v[20:21], v[62:63], v[28:29]
	v_cvt_pk_bf16_f32 v48, v48, v49
	v_cvt_pk_bf16_f32 v49, v50, v51
	v_cvt_pk_bf16_f32 v50, v52, v53
	v_cvt_pk_bf16_f32 v51, v54, v55
	v_cvt_pk_bf16_f32 v52, v56, v57
	v_cvt_pk_bf16_f32 v53, v58, v59
	v_cvt_pk_bf16_f32 v54, v60, v61
	v_cvt_pk_bf16_f32 v55, v62, v63
	global_store_dwordx4 v[36:37], v[48:51], off
	global_store_dwordx4 v[36:37], v[52:55], off offset:1024
	v_add_u32_e32 v34, s12, v34
	v_cmp_le_i32_e32 vcc, s0, v34
	v_mov_b32_e32 v36, v38
	v_mov_b32_e32 v37, v39
	s_or_b64 s[16:17], vcc, s[16:17]
	s_waitcnt vmcnt(2)
	s_andn2_b64 exec, exec, s[16:17]
	s_cbranch_execnz .Lln1_loop
	s_waitcnt vmcnt(0)

; __device__ __forceinline__ unsigned cvt_pk_bf16(float lo, float hi) { const f32x2c v = {lo, hi}; const bf16x2c b = __builtin_convertvector(v, bf16x2c); return __builtin_bit_cast(unsigned, b); }
; __device__ __forceinline__ float bflo(unsigned u) { return __uint_as_float(u << 16); }
; __device__ __forceinline__ float bfhi(unsigned u) { return __uint_as_float(u & 0xffff0000u); }
; __device__ void phase_ln(KP p, const float* g, const float* b, bool final_out, int tid_in, int r0, int r1, int b0) {
;     ...
;     for (int row = r0 + gw; row < r1; row += nw) {
;         bf16_t* xr = Xb + (size_t)row * 1024 + lane * 8;
;         f32x4 x[4]; float s = 0.f;
; #pragma unroll
;         for (int j = 0; j < 2; ++j) { const u32x4v u = *(const u32x4v*)(xr + 512 * j);
;             x[2 * j] = (f32x4){bflo(u[0]), bfhi(u[0]), bflo(u[1]), bfhi(u[1])}; x[2 * j + 1] = (f32x4){bflo(u[2]), bfhi(u[2]), bflo(u[3]), bfhi(u[3])}; }
; #pragma unroll
;         for (int j = 0; j < 4; ++j) s += x[j][0] + x[j][1] + x[j][2] + x[j][3];
;         const float mu = wave_sum(s, lane) * (1.f / 1024.f); float v = 0.f;
; #pragma unroll
;         for (int j = 0; j < 4; ++j) { x[j] = x[j] - mu; v += x[j][0] * x[j][0] + x[j][1] * x[j][1] + x[j][2] * x[j][2] + x[j][3] * x[j][3]; }
;         const float r = rsqrtf(wave_sum(v, lane) * (1.f / 1024.f) + LN_EPS);
; #pragma unroll
;         for (int j = 0; j < 2; ++j) {
;             const f32x4 y0 = x[2 * j] * r * gv[2 * j] + bv[2 * j], y1 = x[2 * j + 1] * r * gv[2 * j + 1] + bv[2 * j + 1];
;             if (final_out) { float* yo = p->out + (size_t)row * 1024 + lane * 8 + 512 * j; __builtin_nontemporal_store(y0, (f32x4*)yo); __builtin_nontemporal_store(y1, (f32x4*)(yo + 4)); }
;             else { u32x4v o; o[0] = cvt_pk_bf16(y0[0], y0[1]); o[1] = cvt_pk_bf16(y0[2], y0[3]); o[2] = cvt_pk_bf16(y1[0], y1[1]); o[3] = cvt_pk_bf16(y1[2], y1[3]);
;                 *(u32x4v*)(xr + 512 * j) = o; }
;         }
;     }
.LBB0_989:
	global_load_dwordx4 v[36:39], v[44:45], off offset:-1024
	global_load_dwordx4 v[48:51], v[44:45], off
	v_mov_b32_e32 v40, 0xba800000
	s_waitcnt vmcnt(0)
.Lln2_loop:
	v_lshlrev_b32_e32 v52, 16, v36
	v_and_b32_e32 v53, 0xffff0000, v36
	v_lshlrev_b32_e32 v54, 16, v37
	v_and_b32_e32 v55, 0xffff0000, v37
	v_lshlrev_b32_e32 v56, 16, v38
	v_and_b32_e32 v57, 0xffff0000, v38
	v_lshlrev_b32_e32 v58, 16, v39
	v_and_b32_e32 v59, 0xffff0000, v39
	v_lshlrev_b32_e32 v60, 16, v48
	v_and_b32_e32 v61, 0xffff0000, v48
	v_lshlrev_b32_e32 v62, 16, v49
	v_and_b32_e32 v63, 0xffff0000, v49
	v_lshlrev_b32_e32 v64, 16, v50
	v_and_b32_e32 v65, 0xffff0000, v50
	v_lshlrev_b32_e32 v66, 16, v51
	v_and_b32_e32 v67, 0xffff0000, v51
	v_lshl_add_u64 v[34:35], v[44:45], 0, s[34:35]
	global_load_dwordx4 v[36:39], v[34:35], off offset:-1024
	global_load_dwordx4 v[48:51], v[34:35], off
	v_pk_add_f32 v[68:69], v[52:53], v[54:55]
	v_pk_add_f32 v[68:69], v[68:69], v[56:57]
	v_pk_add_f32 v[68:69], v[68:69], v[58:59]
	v_pk_add_f32 v[68:69], v[68:69], v[60:61]
	v_pk_add_f32 v[68:69], v[68:69], v[62:63]
	v_pk_add_f32 v[68:69], v[68:69], v[64:65]
	v_pk_add_f32 v[68:69], v[68:69], v[66:67]
	v_add_f32_e32 v43, v68, v69
	s_nop 1
	v_add_f32_dpp v43, v43, v43 quad_perm:[1,0,3,2] row_mask:0xf bank_mask:0xf
	s_nop 1
	v_add_f32_dpp v43, v43, v43 quad_perm:[2,3,0,1] row_mask:0xf bank_mask:0xf
	s_nop 1
	v_add_f32_dpp v43, v43, v43 row_half_mirror row_mask:0xf bank_mask:0xf
	s_nop 1
	v_add_f32_dpp v43, v43, v43 row_mirror row_mask:0xf bank_mask:0xf
	s_nop 1
	v_readlane_b32 vcc_lo, v43, 0
	v_readlane_b32 vcc_hi, v43, 16
	s_nop 1
	v_mov_b32_e32 v8, vcc_lo
	v_add_f32_e32 v8, vcc_hi, v8
	v_readlane_b32 vcc_lo, v43, 32
	v_readlane_b32 vcc_hi, v43, 48
	s_nop 1
	v_add_f32_e32 v8, vcc_lo, v8
	v_add_f32_e32 v43, vcc_hi, v8
	v_mov_b32_e32 v8, v43
	v_mov_b32_e32 v68, v43
	v_pk_fma_f32 v[52:53], v[68:69], v[40:41], v[52:53] op_sel_hi:[0,0,1]
	v_pk_fma_f32 v[54:55], v[68:69], v[40:41], v[54:55] op_sel_hi:[0,0,1]
	v_pk_fma_f32 v[56:57], v[68:69], v[40:41], v[56:57] op_sel_hi:[0,0,1]
	v_pk_fma_f32 v[58:59], v[68:69], v[40:41], v[58:59] op_sel_hi:[0,0,1]
	v_pk_fma_f32 v[60:61], v[68:69], v[40:41], v[60:61] op_sel_hi:[0,0,1]
	v_pk_fma_f32 v[62:63], v[68:69], v[40:41], v[62:63] op_sel_hi:[0,0,1]
	v_pk_fma_f32 v[64:65], v[68:69], v[40:41], v[64:65] op_sel_hi:[0,0,1]
	v_pk_fma_f32 v[66:67], v[68:69], v[40:41], v[66:67] op_sel_hi:[0,0,1]
	v_pk_mul_f32 v[68:69], v[52:53], v[52:53]
	v_pk_fma_f32 v[68:69], v[54:55], v[54:55], v[68:69]
	v_pk_fma_f32 v[68:69], v[56:57], v[56:57], v[68:69]
	v_pk_fma_f32 v[68:69], v[58:59], v[58:59], v[68:69]
	v_pk_fma_f32 v[68:69], v[60:61], v[60:61], v[68:69]
	v_pk_fma_f32 v[68:69], v[62:63], v[62:63], v[68:69]
	v_pk_fma_f32 v[68:69], v[64:65], v[64:65], v[68:69]
	v_pk_fma_f32 v[68:69], v[66:67], v[66:67], v[68:69]
	v_add_f32_e32 v43, v68, v69
	s_nop 1
	v_add_f32_dpp v43, v43, v43 quad_perm:[1,0,3,2] row_mask:0xf bank_mask:0xf
	s_nop 1
	v_add_f32_dpp v43, v43, v43 quad_perm:[2,3,0,1] row_mask:0xf bank_mask:0xf
	s_nop 1
	v_add_f32_dpp v43, v43, v43 row_half_mirror row_mask:0xf bank_mask:0xf
	s_nop 1
	v_add_f32_dpp v43, v43, v43 row_mirror row_mask:0xf bank_mask:0xf
	s_nop 1
	v_readlane_b32 vcc_lo, v43, 0
	v_readlane_b32 vcc_hi, v43, 16
	s_nop 1
	v_mov_b32_e32 v8, vcc_lo
	v_add_f32_e32 v8, vcc_hi, v8
	v_readlane_b32 vcc_lo, v43, 32
	v_readlane_b32 vcc_hi, v43, 48
	s_nop 1
	v_add_f32_e32 v8, vcc_lo, v8
	v_add_f32_e32 v43, vcc_hi, v8
	v_fmamk_f32 v43, v43, 0x3a800000, v248
	v_cmp_gt_f32_e32 vcc, s96, v43
	v_mul_f32_e32 v8, 0x4b800000, v43
	s_nop 0
	v_cndmask_b32_e32 v43, v43, v8, vcc
	v_rsq_f32_e32 v43, v43
	s_nop 0
	v_mul_f32_e32 v8, 0x45800000, v43
	v_cndmask_b32_e32 v68, v43, v8, vcc
	v_pk_mul_f32 v[52:53], v[52:53], v[68:69] op_sel_hi:[1,0]
	v_pk_mul_f32 v[54:55], v[54:55], v[68:69] op_sel_hi:[1,0]
	v_pk_mul_f32 v[56:57], v[56:57], v[68:69] op_sel_hi:[1,0]
	v_pk_mul_f32 v[58:59], v[58:59], v[68:69] op_sel_hi:[1,0]
	v_pk_mul_f32 v[60:61], v[60:61], v[68:69] op_sel_hi:[1,0]
	v_pk_mul_f32 v[62:63], v[62:63], v[68:69] op_sel_hi:[1,0]
	v_pk_mul_f32 v[64:65], v[64:65], v[68:69] op_sel_hi:[1,0]
	v_pk_mul_f32 v[66:67], v[66:67], v[68:69] op_sel_hi:[1,0]
	v_pk_fma_f32 v[52:53], v[4:5], v[52:53], v[14:15]
	v_pk_fma_f32 v[54:55], v[6:7], v[54:55], v[16:17]
	v_pk_fma_f32 v[56:57], v[0:1], v[56:57], v[10:11]
	v_pk_fma_f32 v[58:59], v[2:3], v[58:59], v[12:13]
	v_pk_fma_f32 v[60:61], v[22:23], v[60:61], v[30:31]
	v_pk_fma_f32 v[62:63], v[24:25], v[62:63], v[32:33]
	v_pk_fma_f32 v[64:65], v[18:19], v[64:65], v[26:27]
	v_pk_fma_f32 v[66:67], v[20:21], v[66:67], v[28:29]
	s_and_b64 vcc, exec, s[6:7]
	s_cbranch_vccz .Lln2_f32
	v_cvt_pk_bf16_f32 v52, v52, v53
	v_cvt_pk_bf16_f32 v53, v54, v55
	v_cvt_pk_bf16_f32 v54, v56, v57
	v_cvt_pk_bf16_f32 v55, v58, v59
	v_cvt_pk_bf16_f32 v56, v60, v61
	v_cvt_pk_bf16_f32 v57, v62, v63
	v_cvt_pk_bf16_f32 v58, v64, v65
	v_cvt_pk_bf16_f32 v59, v66, v67
	global_store_dwordx4 v[44:45], v[52:55], off offset:-1024
	global_store_dwordx4 v[44:45], v[56:59], off
	s_waitcnt vmcnt(2)
	s_branch .Lln2_latch
